# prologue weight-transpose task lists start at per-list wave offsets (max 3 items per wave instead of 30 on waves 0/1)
# speedup vs baseline: 1.0120x; 1.0120x over previous
.LBB0_12:
	s_lshl_b32 s46, s7, 7
	s_sub_i32 s46, s48, s46
	s_movk_i32 vcc_lo, 1616
	s_cmp_eq_u32 s7, 3
	s_cselect_b32 vcc_lo, 720, vcc_lo
	s_sub_i32 s46, s46, vcc_lo
	s_cmpk_ge_u32 s46, 0x80
	s_cbranch_scc1 .LBB0_11
	s_add_i32 s8, s7, s21
	s_lshl_b64 s[42:43], s[8:9], 20
	s_lshl_b64 s[44:45], s[8:9], 19
	v_lshl_add_u64 v[40:41], v[24:25], 0, s[42:43]
	v_lshl_add_u64 v[42:43], v[8:9], 0, s[44:45]
	s_lshl_b32 s8, s46, 5
	s_lshl_b32 s41, s60, 5

.LBB0_15:
	s_sub_i32 s41, s48, 1104
	s_cmpk_ge_u32 s41, 0x200
	s_cbranch_scc1 .LBB0_18
	s_lshl_b32 s8, s6, 20
	v_lshl_add_u64 v[40:41], s[8:9], 2, v[26:27]
	s_lshl_b32 s8, s6, 21
	v_lshl_add_u64 v[42:43], v[10:11], 0, s[8:9]
	s_lshl_b32 s7, s41, 5
	s_lshl_b32 s8, s60, 5

.LBB0_18:
	s_sub_i32 s41, s48, 1296
	s_cmp_ge_u32 s41, 48
	s_cbranch_scc1 .LBB0_21
	s_mul_i32 s8, s6, 0x60000
	s_mul_i32 s42, s6, 0x30000
	s_mov_b32 s43, s9
	v_lshl_add_u64 v[40:41], v[28:29], 0, s[8:9]
	v_lshl_add_u64 v[42:43], v[12:13], 0, s[42:43]
	s_lshl_b32 s7, s41, 5
	s_lshl_b32 s8, s60, 5

.LBB0_21:
	s_sub_i32 s46, s48, 1232
	s_cmp_ge_u32 s46, 32
	s_cbranch_scc1 .Lmy_xp_glu
	s_mov_b32 s7, s9
	s_lshl_b64 s[42:43], s[6:7], 18
	s_lshl_b64 s[44:45], s[6:7], 17
	s_lshl_b32 s7, s46, 5
	v_lshl_add_u64 v[40:41], v[30:31], 0, s[42:43]
	v_lshl_add_u64 v[42:43], v[14:15], 0, s[44:45]
	s_lshl_b32 s41, s60, 5
	s_mov_b32 s8, s7

.Lmy_xp_glu:
	s_sub_i32 s46, s48, 1264
	s_cmp_ge_u32 s46, 32
	s_cbranch_scc1 .LBB0_26
	s_lshl_b32 s7, s46, 5
	s_lshl_b32 s41, s60, 5
	s_lshl_b32 s8, s6, 16
	v_lshl_add_u64 v[40:41], s[8:9], 2, v[32:33]
	s_lshl_b32 s8, s6, 17
	v_lshl_add_u64 v[42:43], v[16:17], 0, s[8:9]
	s_mov_b32 s8, s46

; #define LAS __attribute__((address_space(3)))
; __device__ __forceinline__ void p0_transpose_item(const float* W, int K, int N, bf16_t* WT, LAS float* scr, int item, int lane) {
;     const int nblk = N / 32, kb = item / nblk, nb = item % nblk, k0 = 64 * kb, n0 = 32 * nb;
;     float tv[32];
; #pragma unroll
;     for (int i = 0; i < 32; ++i) tv[i] = W[(size_t)(k0 + 2 * i + (lane >> 5)) * N + n0 + (lane & 31)];
.LBB0_28:
	v_cndmask_b32_e64 v2, 0, 1, s[34:35]
	v_cmp_ne_u32_e64 s[6:7], 1, v2
	s_lshl_b32 s58, s53, 1
	s_sub_i32 s58, s48, s58
	s_sub_i32 s58, s58, 2000
	s_cmp_ge_u32 s58, 2
	s_cbranch_scc1 .LBB0_27
	s_add_i32 s8, s53, s41
	s_lshl_b64 s[42:43], s[8:9], 14
	s_lshr_b32 s8, s53, 1
	s_and_b32 s44, s8, 2
	s_or_b32 s44, s44, s21
	s_lshl_b32 s44, s44, 15
	s_add_u32 s44, s49, s44
	s_addc_u32 s45, s50, 0
	s_lshl_b32 s46, s53, 12
	s_and_b32 s56, s46, 0x3000
	s_lshl_b32 s46, s56, 1
	s_add_u32 s44, s44, s46
	s_addc_u32 s45, s45, 0
	v_lshlrev_b32_e32 v2, 1, v4
	s_lshl_b32 s54, s58, 5
	v_lshl_add_u64 v[40:41], v[34:35], 0, s[42:43]
	v_lshl_add_u64 v[42:43], s[44:45], 0, v[2:3]
	s_lshl_b32 s55, s60, 5
	s_mov_b32 s57, s54
.LBB0_30:
	s_lshr_b32 s44, s58, 31
	s_add_i32 s44, s58, s44
	s_lshl_b32 s44, s44, 5
	s_and_b32 s46, s44, 0xffffffc0
	v_or_b32_e32 v54, s46, v5
	s_sub_i32 s44, s57, s46
	v_or_b32_e32 v58, 14, v54
	v_or_b32_e32 v60, 16, v54
	v_or_b32_e32 v62, 18, v54
	v_or_b32_e32 v64, 20, v54
	v_or_b32_e32 v66, 22, v54
	v_or_b32_e32 v68, 24, v54
	v_or_b32_e32 v72, 26, v54
	v_or_b32_e32 v74, 28, v54
	v_or_b32_e32 v76, 30, v54
	v_or_b32_e32 v92, 32, v54
	v_or_b32_e32 v94, 34, v54
	v_or_b32_e32 v96, 36, v54
	v_or_b32_e32 v98, 38, v54
	s_ashr_i32 s45, s44, 31
	v_ashrrev_i32_e32 v55, 31, v54
	v_or_b32_e32 v44, 2, v54
	v_or_b32_e32 v46, 4, v54
	v_or_b32_e32 v48, 6, v54
	v_or_b32_e32 v50, 8, v54
	v_or_b32_e32 v52, 10, v54
	v_or_b32_e32 v56, 12, v54
	v_or_b32_e32 v100, 40, v54
	v_or_b32_e32 v102, 42, v54
	v_or_b32_e32 v104, 44, v54
	v_or_b32_e32 v106, 46, v54
	v_or_b32_e32 v108, 48, v54
	v_or_b32_e32 v110, 50, v54
	v_or_b32_e32 v112, 52, v54
	v_or_b32_e32 v114, 54, v54
	v_or_b32_e32 v116, 56, v54
	v_or_b32_e32 v118, 58, v54
	v_or_b32_e32 v120, 60, v54
	v_or_b32_e32 v122, 62, v54
	v_ashrrev_i32_e32 v59, 31, v58
	v_ashrrev_i32_e32 v61, 31, v60
	v_ashrrev_i32_e32 v63, 31, v62
	v_ashrrev_i32_e32 v65, 31, v64
	v_ashrrev_i32_e32 v67, 31, v66
	v_ashrrev_i32_e32 v69, 31, v68
	v_ashrrev_i32_e32 v73, 31, v72
	v_ashrrev_i32_e32 v75, 31, v74
	v_ashrrev_i32_e32 v77, 31, v76
	v_ashrrev_i32_e32 v93, 31, v92
	v_ashrrev_i32_e32 v95, 31, v94
	v_ashrrev_i32_e32 v97, 31, v96
	v_ashrrev_i32_e32 v99, 31, v98
	v_lshl_add_u64 v[124:125], s[44:45], 2, v[40:41]
	v_lshlrev_b64 v[54:55], 8, v[54:55]
	v_ashrrev_i32_e32 v45, 31, v44
	v_ashrrev_i32_e32 v47, 31, v46
	v_ashrrev_i32_e32 v49, 31, v48
	v_ashrrev_i32_e32 v51, 31, v50
	v_ashrrev_i32_e32 v53, 31, v52
	v_ashrrev_i32_e32 v57, 31, v56
	v_ashrrev_i32_e32 v101, 31, v100
	v_ashrrev_i32_e32 v103, 31, v102
	v_ashrrev_i32_e32 v105, 31, v104
	v_ashrrev_i32_e32 v107, 31, v106
	v_ashrrev_i32_e32 v109, 31, v108
	v_ashrrev_i32_e32 v111, 31, v110
	v_ashrrev_i32_e32 v113, 31, v112
	v_ashrrev_i32_e32 v115, 31, v114
	v_ashrrev_i32_e32 v117, 31, v116
	v_ashrrev_i32_e32 v119, 31, v118
	v_ashrrev_i32_e32 v121, 31, v120
	v_ashrrev_i32_e32 v123, 31, v122
	v_lshlrev_b64 v[58:59], 8, v[58:59]
	v_lshlrev_b64 v[60:61], 8, v[60:61]
	v_lshlrev_b64 v[62:63], 8, v[62:63]
	v_lshlrev_b64 v[64:65], 8, v[64:65]
	v_lshlrev_b64 v[66:67], 8, v[66:67]
	v_lshlrev_b64 v[68:69], 8, v[68:69]
	v_lshlrev_b64 v[72:73], 8, v[72:73]
	v_lshlrev_b64 v[74:75], 8, v[74:75]
	v_lshlrev_b64 v[76:77], 8, v[76:77]
	v_lshlrev_b64 v[92:93], 8, v[92:93]
	v_lshlrev_b64 v[94:95], 8, v[94:95]
	v_lshlrev_b64 v[96:97], 8, v[96:97]
	v_lshlrev_b64 v[98:99], 8, v[98:99]
	v_lshl_add_u64 v[54:55], v[124:125], 0, v[54:55]
	v_lshlrev_b64 v[44:45], 8, v[44:45]
	v_lshlrev_b64 v[46:47], 8, v[46:47]
	v_lshlrev_b64 v[48:49], 8, v[48:49]
	v_lshlrev_b64 v[50:51], 8, v[50:51]
	v_lshlrev_b64 v[52:53], 8, v[52:53]
	v_lshlrev_b64 v[56:57], 8, v[56:57]
	v_lshlrev_b64 v[100:101], 8, v[100:101]
	v_lshlrev_b64 v[102:103], 8, v[102:103]
	v_lshlrev_b64 v[104:105], 8, v[104:105]
	v_lshlrev_b64 v[106:107], 8, v[106:107]
	v_lshlrev_b64 v[108:109], 8, v[108:109]
	v_lshlrev_b64 v[110:111], 8, v[110:111]
	v_lshlrev_b64 v[112:113], 8, v[112:113]
	v_lshlrev_b64 v[114:115], 8, v[114:115]
	v_lshlrev_b64 v[116:117], 8, v[116:117]
	v_lshlrev_b64 v[118:119], 8, v[118:119]
	v_lshlrev_b64 v[120:121], 8, v[120:121]
	v_lshlrev_b64 v[122:123], 8, v[122:123]
	v_lshl_add_u64 v[58:59], v[124:125], 0, v[58:59]
	v_lshl_add_u64 v[60:61], v[124:125], 0, v[60:61]
	v_lshl_add_u64 v[62:63], v[124:125], 0, v[62:63]
	v_lshl_add_u64 v[64:65], v[124:125], 0, v[64:65]
	v_lshl_add_u64 v[66:67], v[124:125], 0, v[66:67]
	v_lshl_add_u64 v[68:69], v[124:125], 0, v[68:69]
	v_lshl_add_u64 v[72:73], v[124:125], 0, v[72:73]
	v_lshl_add_u64 v[74:75], v[124:125], 0, v[74:75]
	v_lshl_add_u64 v[76:77], v[124:125], 0, v[76:77]
	v_lshl_add_u64 v[92:93], v[124:125], 0, v[92:93]
	v_lshl_add_u64 v[94:95], v[124:125], 0, v[94:95]
	v_lshl_add_u64 v[96:97], v[124:125], 0, v[96:97]
	v_lshl_add_u64 v[98:99], v[124:125], 0, v[98:99]
	v_lshl_add_u64 v[44:45], v[124:125], 0, v[44:45]
	v_lshl_add_u64 v[46:47], v[124:125], 0, v[46:47]
	v_lshl_add_u64 v[48:49], v[124:125], 0, v[48:49]
	v_lshl_add_u64 v[50:51], v[124:125], 0, v[50:51]
	v_lshl_add_u64 v[52:53], v[124:125], 0, v[52:53]
	v_lshl_add_u64 v[56:57], v[124:125], 0, v[56:57]
	v_lshl_add_u64 v[100:101], v[124:125], 0, v[100:101]
	v_lshl_add_u64 v[102:103], v[124:125], 0, v[102:103]
	v_lshl_add_u64 v[104:105], v[124:125], 0, v[104:105]
	v_lshl_add_u64 v[106:107], v[124:125], 0, v[106:107]
	v_lshl_add_u64 v[108:109], v[124:125], 0, v[108:109]
	v_lshl_add_u64 v[110:111], v[124:125], 0, v[110:111]
; #define LAS __attribute__((address_space(3)))
; __device__ __forceinline__ unsigned cvt_pk_bf16(float lo, float hi) { unsigned r; asm volatile("v_cvt_pk_bf16_f32 %0, %1, %2" : "=v"(r) : "v"(lo), "v"(hi)); return r; }
; __device__ __forceinline__ void p0_transpose_item(const float* W, int K, int N, bf16_t* WT, LAS float* scr, int item, int lane) {
;     const int nblk = N / 32, kb = item / nblk, nb = item % nblk, k0 = 64 * kb, n0 = 32 * nb;
;     float tv[32];
; #pragma unroll
;     for (int i = 0; i < 32; ++i) tv[i] = W[(size_t)(k0 + 2 * i + (lane >> 5)) * N + n0 + (lane & 31)];
; #pragma unroll
;     for (int i = 0; i < 32; ++i) scr[(2 * i + (lane >> 5)) * 33 + (lane & 31)] = tv[i];
;     asm volatile("s_waitcnt lgkmcnt(0)" ::: "memory");
;     const int c = lane & 7;
; #pragma unroll
;     for (int j = 0; j < 4; ++j) { const int n = (lane >> 3) + 8 * j; const LAS float* s = scr + (8 * c) * 33 + n;
;         u32x4 o; o.x = cvt_pk_bf16(s[0 * 33], s[1 * 33]); o.y = cvt_pk_bf16(s[2 * 33], s[3 * 33]); o.z = cvt_pk_bf16(s[4 * 33], s[5 * 33]); o.w = cvt_pk_bf16(s[6 * 33], s[7 * 33]);
;         *(u32x4*)(WT + (size_t)(n0 + n) * K + k0 + 8 * c) = o; }
;     asm volatile("s_waitcnt lgkmcnt(0)" ::: "memory");
; }
	v_lshl_add_u64 v[112:113], v[124:125], 0, v[112:113]
	v_lshl_add_u64 v[114:115], v[124:125], 0, v[114:115]
	v_lshl_add_u64 v[116:117], v[124:125], 0, v[116:117]
	v_lshl_add_u64 v[118:119], v[124:125], 0, v[118:119]
	v_lshl_add_u64 v[120:121], v[124:125], 0, v[120:121]
	v_lshl_add_u64 v[122:123], v[124:125], 0, v[122:123]
	global_load_dword v124, v[54:55], off
	global_load_dword v125, v[44:45], off
	global_load_dword v126, v[46:47], off
	global_load_dword v127, v[48:49], off
	global_load_dword v128, v[50:51], off
	global_load_dword v129, v[52:53], off
	global_load_dword v130, v[56:57], off
	s_nop 0
	global_load_dword v58, v[58:59], off
	s_nop 0
	global_load_dword v59, v[60:61], off
	s_nop 0
	global_load_dword v60, v[62:63], off
	global_load_dword v61, v[64:65], off
	s_nop 0
	global_load_dword v62, v[66:67], off
	global_load_dword v63, v[68:69], off
	global_load_dword v64, v[72:73], off
	global_load_dword v65, v[74:75], off
	s_nop 0
	global_load_dword v66, v[76:77], off
	global_load_dword v67, v[92:93], off
	global_load_dword v68, v[94:95], off
	global_load_dword v69, v[96:97], off
	global_load_dword v72, v[98:99], off
	global_load_dword v73, v[100:101], off
	global_load_dword v74, v[102:103], off
	global_load_dword v75, v[104:105], off
	global_load_dword v76, v[106:107], off
	global_load_dword v77, v[108:109], off
	global_load_dword v92, v[110:111], off
	global_load_dword v93, v[112:113], off
	global_load_dword v94, v[114:115], off
	global_load_dword v95, v[116:117], off
	global_load_dword v96, v[118:119], off
	global_load_dword v97, v[120:121], off
	global_load_dword v98, v[122:123], off
	v_add_u32_e32 v50, s44, v78
	v_add_u32_e32 v46, 8, v50
	s_ashr_i32 s47, s46, 31
	v_ashrrev_i32_e32 v47, 31, v46
	s_waitcnt vmcnt(0)
	ds_write2_b32 v71, v124, v125 offset1:66
	ds_write2_b32 v71, v126, v127 offset0:132 offset1:198
	ds_write2_b32 v81, v128, v129 offset0:8 offset1:74
	ds_write2_b32 v81, v130, v58 offset0:140 offset1:206
	ds_write2_b32 v82, v59, v60 offset0:16 offset1:82
	ds_write2_b32 v82, v61, v62 offset0:148 offset1:214
	ds_write2_b32 v83, v63, v64 offset0:24 offset1:90
	ds_write2_b32 v83, v65, v66 offset0:156 offset1:222
	ds_write2_b32 v84, v67, v68 offset0:32 offset1:98
	ds_write2_b32 v84, v69, v72 offset0:164 offset1:230
	ds_write2_b32 v85, v73, v74 offset0:40 offset1:106
	ds_write2_b32 v85, v75, v76 offset0:172 offset1:238
	ds_write2_b32 v86, v77, v92 offset0:48 offset1:114
	ds_write2_b32 v86, v93, v94 offset0:180 offset1:246
	ds_write2_b32 v87, v95, v96 offset0:56 offset1:122
	ds_write2_b32 v87, v97, v98 offset0:188 offset1:254
	v_lshl_add_u64 v[44:45], s[46:47], 1, v[42:43]
	v_add_u32_e32 v48, 16, v50
	v_lshlrev_b64 v[46:47], 7, v[46:47]
	s_waitcnt lgkmcnt(0)
	v_ashrrev_i32_e32 v51, 31, v50
	v_ashrrev_i32_e32 v49, 31, v48
	v_lshl_add_u64 v[56:57], v[44:45], 0, v[46:47]
	ds_read2_b32 v[46:47], v79 offset1:33
	v_lshlrev_b64 v[52:53], 7, v[50:51]
	v_lshlrev_b64 v[54:55], 7, v[48:49]
	s_waitcnt lgkmcnt(0)
	v_cvt_pk_bf16_f32 v46, v46, v47
	ds_read2_b32 v[48:49], v79 offset0:66 offset1:99
	v_lshl_add_u64 v[52:53], v[44:45], 0, v[52:53]
	s_waitcnt lgkmcnt(0)
	v_cvt_pk_bf16_f32 v47, v48, v49
	ds_read2_b32 v[48:49], v79 offset0:132 offset1:165
	s_waitcnt lgkmcnt(0)
	v_cvt_pk_bf16_f32 v48, v48, v49
	ds_read2_b32 v[58:59], v79 offset0:198 offset1:231
	s_waitcnt lgkmcnt(0)
	v_cvt_pk_bf16_f32 v49, v58, v59
	flat_store_dwordx4 v[52:53], v[46:49]
	ds_read2_b32 v[46:47], v79 offset0:8 offset1:41
	v_lshl_add_u64 v[54:55], v[44:45], 0, v[54:55]
	s_waitcnt lgkmcnt(0)
	v_cvt_pk_bf16_f32 v46, v46, v47
	ds_read2_b32 v[48:49], v79 offset0:74 offset1:107
	s_waitcnt lgkmcnt(0)
	v_cvt_pk_bf16_f32 v47, v48, v49
	ds_read2_b32 v[48:49], v79 offset0:140 offset1:173
	s_waitcnt lgkmcnt(0)
	v_cvt_pk_bf16_f32 v48, v48, v49
	ds_read2_b32 v[52:53], v79 offset0:206 offset1:239
	s_waitcnt lgkmcnt(0)
	v_cvt_pk_bf16_f32 v49, v52, v53
	flat_store_dwordx4 v[56:57], v[46:49]
	ds_read2_b32 v[46:47], v79 offset0:16 offset1:49
	v_add_u32_e32 v50, 24, v50
	s_waitcnt lgkmcnt(0)
	v_cvt_pk_bf16_f32 v46, v46, v47
	ds_read2_b32 v[48:49], v79 offset0:82 offset1:115
	s_waitcnt lgkmcnt(0)
	v_cvt_pk_bf16_f32 v47, v48, v49
	ds_read2_b32 v[48:49], v79 offset0:148 offset1:181
	s_waitcnt lgkmcnt(0)
	v_cvt_pk_bf16_f32 v48, v48, v49
	ds_read2_b32 v[52:53], v79 offset0:214 offset1:247
	s_waitcnt lgkmcnt(0)
	v_cvt_pk_bf16_f32 v49, v52, v53
	flat_store_dwordx4 v[54:55], v[46:49]
	ds_read2_b32 v[46:47], v79 offset0:24 offset1:57
	v_ashrrev_i32_e32 v51, 31, v50
	s_waitcnt lgkmcnt(0)
	v_cvt_pk_bf16_f32 v46, v46, v47
	ds_read2_b32 v[48:49], v79 offset0:90 offset1:123
	v_lshlrev_b64 v[50:51], 7, v[50:51]
	s_waitcnt lgkmcnt(0)
	v_cvt_pk_bf16_f32 v47, v48, v49
	ds_read2_b32 v[48:49], v79 offset0:156 offset1:189
	v_lshl_add_u64 v[44:45], v[44:45], 0, v[50:51]
	s_waitcnt lgkmcnt(0)
	v_cvt_pk_bf16_f32 v48, v48, v49
	ds_read2_b32 v[52:53], v79 offset0:222 offset1:255
	s_waitcnt lgkmcnt(0)
	v_cvt_pk_bf16_f32 v49, v52, v53
	flat_store_dwordx4 v[44:45], v[46:49]
	s_waitcnt lgkmcnt(0)
	s_add_i32 s58, s58, s60
	s_add_i32 s57, s57, s55
	s_cmp_gt_i32 s58, 1
	s_cbranch_scc0 .LBB0_30
	s_add_i32 s8, s8, s21
	s_or_b32 s8, s8, 1
	s_lshl_b64 s[44:45], s[8:9], 15
	s_add_u32 s8, s49, s44
	s_addc_u32 s45, s50, s45
	s_lshl_b32 s44, s56, 1
	s_add_u32 s44, s8, s44
	s_addc_u32 s45, s45, 0
	v_lshl_add_u64 v[40:41], v[36:37], 0, s[42:43]
	v_lshl_add_u64 v[42:43], s[44:45], 0, v[2:3]
	s_lshl_b32 s8, s53, 1
	s_sub_i32 s8, s48, s8
	s_sub_i32 s8, s8, 2000

.LBB0_35:
	s_lshl_b32 s47, s41, 1
	s_sub_i32 s47, s48, s47
	s_sub_i32 s47, s47, 1344
	s_cmp_ge_u32 s47, 2
	s_cbranch_scc1 .LBB0_34
	s_add_i32 s8, s41, s21
	s_lshl_b64 s[42:43], s[8:9], 14
	v_lshl_add_u64 v[40:41], v[38:39], 0, s[42:43]
	s_lshl_b64 s[42:43], s[8:9], 13
	v_lshl_add_u64 v[42:43], v[18:19], 0, s[42:43]
	s_lshl_b32 s8, s47, 5
	s_lshl_b32 s46, s60, 5

; #define LAS __attribute__((address_space(3)))
; __device__ __forceinline__ float siluf(float x) { return x * __builtin_amdgcn_rcpf(1.f + __expf(-x)); }
; __global__ void __launch_bounds__(512, 2) fwd_kernel(KArgs a) {
;     ...
;         for (int r_ = 0; r_ < REP_PRO; ++r_)
;         for (int l = 0; l < (G == 256 ? 1 : 2); ++l) XPOSE_LAYER(l, gw, NGW);
;         __syncthreads();
;         {
;             LAS float* cact = (LAS float*)lds;
;             for (int i = tid; i < 17 * 1024; i += 512) { const int r = i >> 10, k = i & 1023; const float v = r < 16 ? a.in[1][r * 1024 + k] : a.in[3][k]; cact[i] = siluf(v); }
.LBB0_40:
	v_add_u32_e32 v2, s20, v2
	s_movk_i32 s8, 0x2fff
	v_cmp_lt_i32_e32 vcc, s8, v2
	flat_store_dwordx4 v[40:41], v[88:91]
	s_or_b64 s[40:41], vcc, s[40:41]
	v_lshl_add_u64 v[40:41], v[40:41], 0, s[36:37]
	s_andn2_b64 exec, exec, s[40:41]
	s_cbranch_execnz .LBB0_40
	s_branch .LBB0_6
	s_branch .Lmy_pad_LBB041
	s_nop 0
	s_nop 0
	s_nop 0
	s_nop 0
	s_nop 0
	s_nop 0
	s_nop 0
.Lmy_pad_LBB041:
.LBB0_41:
	s_movk_i32 s4, 0x4400
	v_cmp_gt_i32_e32 vcc, s4, v70
	s_waitcnt lgkmcnt(0)
	s_barrier
	s_and_saveexec_b64 s[4:5], vcc
	v_readlane_b32 s36, v251, 56
	v_readlane_b32 s38, v251, 58
	v_readlane_b32 s39, v251, 59
	v_readlane_b32 s42, v251, 62
	v_readlane_b32 s43, v251, 63
	v_readlane_b32 s37, v251, 57
	v_readlane_b32 s40, v251, 60
	v_readlane_b32 s41, v251, 61
	v_readlane_b32 s44, v252, 0
	v_readlane_b32 s45, v252, 1
	v_readlane_b32 s46, v252, 2
	v_readlane_b32 s47, v252, 3
	v_readlane_b32 s48, v252, 4
	v_readlane_b32 s49, v252, 5
	v_readlane_b32 s50, v252, 6
	v_readlane_b32 s51, v252, 7
	s_cbranch_execz .LBB0_44
	v_mov_b32_e32 v2, s38
	v_mov_b32_e32 v3, s39
	v_ashrrev_i32_e32 v71, 31, v70
	v_lshl_add_u64 v[2:3], v[70:71], 2, v[2:3]
	v_lshl_add_u32 v6, v70, 2, 0
	s_mov_b64 s[6:7], 0
	v_mov_b32_e32 v5, 0
	s_mov_b64 s[8:9], 0x800
	s_movk_i32 s10, 0x41ff
	v_mov_b32_e32 v7, v70
	s_movk_i32 s11, 0x4000
